# prep: w_in/w_out transpose tiles with 8 loads / 8 LDS reads in flight, x->bf16 conversion with a 7-deep rolling load window (same arithmetic)
# speedup vs baseline: 1.0092x; 1.0092x over previous
; DI void prep_transpose_tile(const float* __restrict__ src, u16* __restrict__ dst, int R, int C, const float* __restrict__ g, int tr, int tc, float* lds) {
;     ...
;   for (int i = tid; i < 4096; i += NTHR) {
;     int r = i >> 6, c = i & 63, gr = tr * 64 + r, gc = tc * 64 + c;
;     float v = 0.f;
;     if (gr < R && gc < C) { v = src[(size_t)gr * C + gc]; if (g) v *= g[gr]; }
;     lds[r * 65 + c] = v;
;   }
.LBB0_29:
	s_add_i32 s0, s48, 0xfffffd40
	s_ashr_i32 s11, s10, 31
	v_mov_b32_e32 v1, v184
	s_lshl_b64 s[4:5], s[10:11], 20
	s_lshr_b32 s11, s0, 4
	s_and_b32 s18, s48, 15
	s_nop 0
	v_cmp_gt_i32_e32 vcc, s22, v1
	s_and_saveexec_b64 s[12:13], vcc
	s_cbranch_execz .LBB0_34
	s_lshl_b64 s[0:1], s[4:5], 2
	v_lshlrev_b32_e32 v2, 2, v1
	s_add_u32 s0, s84, s0
	v_and_b32_e32 v6, 0xfc, v2
	s_addc_u32 s1, s85, s1
	v_lshl_or_b32 v2, s18, 8, v6
	s_lshl_b32 s19, s11, 6
	v_lshl_add_u64 v[4:5], s[0:1], 0, v[2:3]
	v_add_u32_e32 v2, 0, v6
	s_mov_b64 s[14:15], 0
	v_mov_b32_e32 v8, v1
	v_ashrrev_i32_e32 v36, 6, v1
	v_add_u32_e32 v6, s19, v36
	v_cmp_gt_i32_e64 s[0:1], s44, v6
	v_mad_u32_u24 v28, v36, s26, v2
	v_mov_b32_e32 v20, 0
	s_and_saveexec_b64 s[16:17], s[0:1]
	v_ashrrev_i32_e32 v7, 31, v6
	v_lshlrev_b64 v[6:7], 12, v[6:7]
	v_lshl_add_u64 v[6:7], v[4:5], 0, v[6:7]
	global_load_dword v20, v[6:7], off
	s_or_b64 exec, exec, s[16:17]
	v_add_u32_e32 v37, 8, v36
	v_add_u32_e32 v6, s19, v37
	v_cmp_gt_i32_e64 s[0:1], s44, v6
	v_mad_u32_u24 v29, v37, s26, v2
	v_mov_b32_e32 v21, 0
	s_and_saveexec_b64 s[16:17], s[0:1]
	v_ashrrev_i32_e32 v7, 31, v6
	v_lshlrev_b64 v[6:7], 12, v[6:7]
	v_lshl_add_u64 v[6:7], v[4:5], 0, v[6:7]
	global_load_dword v21, v[6:7], off
	s_or_b64 exec, exec, s[16:17]
	v_add_u32_e32 v37, 16, v36
	v_add_u32_e32 v6, s19, v37
	v_cmp_gt_i32_e64 s[0:1], s44, v6
	v_mad_u32_u24 v30, v37, s26, v2
	v_mov_b32_e32 v22, 0
	s_and_saveexec_b64 s[16:17], s[0:1]
	v_ashrrev_i32_e32 v7, 31, v6
	v_lshlrev_b64 v[6:7], 12, v[6:7]
	v_lshl_add_u64 v[6:7], v[4:5], 0, v[6:7]
	global_load_dword v22, v[6:7], off
	s_or_b64 exec, exec, s[16:17]
	v_add_u32_e32 v37, 24, v36
	v_add_u32_e32 v6, s19, v37
	v_cmp_gt_i32_e64 s[0:1], s44, v6
	v_mad_u32_u24 v31, v37, s26, v2
	v_mov_b32_e32 v23, 0
	s_and_saveexec_b64 s[16:17], s[0:1]
	v_ashrrev_i32_e32 v7, 31, v6
	v_lshlrev_b64 v[6:7], 12, v[6:7]
	v_lshl_add_u64 v[6:7], v[4:5], 0, v[6:7]
	global_load_dword v23, v[6:7], off
	s_or_b64 exec, exec, s[16:17]
	v_add_u32_e32 v37, 32, v36
	v_add_u32_e32 v6, s19, v37
	v_cmp_gt_i32_e64 s[0:1], s44, v6
	v_mad_u32_u24 v32, v37, s26, v2
	v_mov_b32_e32 v24, 0
	s_and_saveexec_b64 s[16:17], s[0:1]
	v_ashrrev_i32_e32 v7, 31, v6
	v_lshlrev_b64 v[6:7], 12, v[6:7]
	v_lshl_add_u64 v[6:7], v[4:5], 0, v[6:7]
	global_load_dword v24, v[6:7], off
	s_or_b64 exec, exec, s[16:17]
	v_add_u32_e32 v37, 40, v36
	v_add_u32_e32 v6, s19, v37
	v_cmp_gt_i32_e64 s[0:1], s44, v6
	v_mad_u32_u24 v33, v37, s26, v2
	v_mov_b32_e32 v25, 0
	s_and_saveexec_b64 s[16:17], s[0:1]
	v_ashrrev_i32_e32 v7, 31, v6
	v_lshlrev_b64 v[6:7], 12, v[6:7]
	v_lshl_add_u64 v[6:7], v[4:5], 0, v[6:7]
	global_load_dword v25, v[6:7], off
	s_or_b64 exec, exec, s[16:17]
	v_add_u32_e32 v37, 48, v36
	v_add_u32_e32 v6, s19, v37
	v_cmp_gt_i32_e64 s[0:1], s44, v6
	v_mad_u32_u24 v34, v37, s26, v2
	v_mov_b32_e32 v26, 0
	s_and_saveexec_b64 s[16:17], s[0:1]
	v_ashrrev_i32_e32 v7, 31, v6
	v_lshlrev_b64 v[6:7], 12, v[6:7]
	v_lshl_add_u64 v[6:7], v[4:5], 0, v[6:7]
	global_load_dword v26, v[6:7], off
	s_or_b64 exec, exec, s[16:17]
	v_add_u32_e32 v37, 56, v36
	v_add_u32_e32 v6, s19, v37
	v_cmp_gt_i32_e64 s[0:1], s44, v6
	v_mad_u32_u24 v35, v37, s26, v2
	v_mov_b32_e32 v27, 0
	s_and_saveexec_b64 s[16:17], s[0:1]
	v_ashrrev_i32_e32 v7, 31, v6
	v_lshlrev_b64 v[6:7], 12, v[6:7]
	v_lshl_add_u64 v[6:7], v[4:5], 0, v[6:7]
	global_load_dword v27, v[6:7], off
	s_or_b64 exec, exec, s[16:17]
	s_waitcnt vmcnt(0)
	ds_write_b32 v28, v20
	ds_write_b32 v29, v21
	ds_write_b32 v30, v22
	ds_write_b32 v31, v23
	ds_write_b32 v32, v24
	ds_write_b32 v33, v25
	ds_write_b32 v34, v26
	ds_write_b32 v35, v27
; DI u16 f2bf(float x) { unsigned u = __float_as_uint(x); u += 0x7fffu + ((u >> 16) & 1u); return (u16)(u >> 16); }
; DI void prep_transpose_tile(const float* __restrict__ src, u16* __restrict__ dst, int R, int C, const float* __restrict__ g, int tr, int tc, float* lds) {
;     ...
;   __syncthreads();
;   for (int i = tid; i < 4096; i += NTHR) {
;     int c = i >> 6, r = i & 63, gr = tr * 64 + r, gc = tc * 64 + c;
;     if (gr < R && gc < C) dst[(size_t)gc * R + gr] = f2bf(lds[r * 65 + c]);
;   }
.LBB0_34:
	s_or_b64 exec, exec, s[12:13]
	s_waitcnt lgkmcnt(0)
	s_barrier
	s_and_saveexec_b64 s[0:1], vcc
	s_cbranch_execz .LBB0_39
	s_lshl_b64 s[4:5], s[4:5], 1
	v_readlane_b32 s2, v254, 20
	v_and_b32_e32 v2, 63, v1
	s_add_u32 s4, s2, s4
	v_readlane_b32 s2, v254, 21
	v_mad_u32_u24 v8, v2, s26, 0
	v_lshlrev_b32_e32 v2, 1, v2
	s_addc_u32 s5, s2, s5
	v_lshl_or_b32 v2, s11, 7, v2
	s_lshl_b32 s14, s18, 6
	v_lshl_add_u64 v[4:5], s[4:5], 0, v[2:3]
	s_mov_b64 s[4:5], 0
	v_ashrrev_i32_e32 v36, 6, v1
	v_mov_b32_e32 v28, v36
	v_lshl_add_u32 v37, v28, 2, v8
	ds_read_b32 v20, v37
	v_add_u32_e32 v29, 8, v36
	v_lshl_add_u32 v37, v29, 2, v8
	ds_read_b32 v21, v37
	v_add_u32_e32 v30, 16, v36
	v_lshl_add_u32 v37, v30, 2, v8
	ds_read_b32 v22, v37
	v_add_u32_e32 v31, 24, v36
	v_lshl_add_u32 v37, v31, 2, v8
	ds_read_b32 v23, v37
	v_add_u32_e32 v32, 32, v36
	v_lshl_add_u32 v37, v32, 2, v8
	ds_read_b32 v24, v37
	v_add_u32_e32 v33, 40, v36
	v_lshl_add_u32 v37, v33, 2, v8
	ds_read_b32 v25, v37
	v_add_u32_e32 v34, 48, v36
	v_lshl_add_u32 v37, v34, 2, v8
	ds_read_b32 v26, v37
	v_add_u32_e32 v35, 56, v36
	v_lshl_add_u32 v37, v35, 2, v8
	ds_read_b32 v27, v37
	v_add_u32_e32 v6, s14, v28
	v_cmp_gt_i32_e32 vcc, s44, v6
	s_and_saveexec_b64 s[12:13], vcc
	v_ashrrev_i32_e32 v7, 31, v6
	v_lshlrev_b64 v[6:7], 11, v[6:7]
	v_lshl_add_u64 v[6:7], v[4:5], 0, v[6:7]
	s_waitcnt lgkmcnt(7)
	v_bfe_u32 v9, v20, 16, 1
	v_add3_u32 v20, v20, v9, s28
	global_store_short_d16_hi v[6:7], v20, off
	s_or_b64 exec, exec, s[12:13]
	v_add_u32_e32 v6, s14, v29
	v_cmp_gt_i32_e32 vcc, s44, v6
	s_and_saveexec_b64 s[12:13], vcc
	v_ashrrev_i32_e32 v7, 31, v6
	v_lshlrev_b64 v[6:7], 11, v[6:7]
	v_lshl_add_u64 v[6:7], v[4:5], 0, v[6:7]
	s_waitcnt lgkmcnt(6)
	v_bfe_u32 v9, v21, 16, 1
	v_add3_u32 v21, v21, v9, s28
	global_store_short_d16_hi v[6:7], v21, off
	s_or_b64 exec, exec, s[12:13]
	v_add_u32_e32 v6, s14, v30
	v_cmp_gt_i32_e32 vcc, s44, v6
	s_and_saveexec_b64 s[12:13], vcc
	v_ashrrev_i32_e32 v7, 31, v6
	v_lshlrev_b64 v[6:7], 11, v[6:7]
	v_lshl_add_u64 v[6:7], v[4:5], 0, v[6:7]
	s_waitcnt lgkmcnt(5)
	v_bfe_u32 v9, v22, 16, 1
	v_add3_u32 v22, v22, v9, s28
	global_store_short_d16_hi v[6:7], v22, off
	s_or_b64 exec, exec, s[12:13]
	v_add_u32_e32 v6, s14, v31
	v_cmp_gt_i32_e32 vcc, s44, v6
	s_and_saveexec_b64 s[12:13], vcc
	v_ashrrev_i32_e32 v7, 31, v6
	v_lshlrev_b64 v[6:7], 11, v[6:7]
	v_lshl_add_u64 v[6:7], v[4:5], 0, v[6:7]
	s_waitcnt lgkmcnt(4)
	v_bfe_u32 v9, v23, 16, 1
	v_add3_u32 v23, v23, v9, s28
	global_store_short_d16_hi v[6:7], v23, off
	s_or_b64 exec, exec, s[12:13]
	v_add_u32_e32 v6, s14, v32
	v_cmp_gt_i32_e32 vcc, s44, v6
	s_and_saveexec_b64 s[12:13], vcc
	v_ashrrev_i32_e32 v7, 31, v6
	v_lshlrev_b64 v[6:7], 11, v[6:7]
	v_lshl_add_u64 v[6:7], v[4:5], 0, v[6:7]
	s_waitcnt lgkmcnt(3)
	v_bfe_u32 v9, v24, 16, 1
	v_add3_u32 v24, v24, v9, s28
	global_store_short_d16_hi v[6:7], v24, off
	s_or_b64 exec, exec, s[12:13]
	v_add_u32_e32 v6, s14, v33
	v_cmp_gt_i32_e32 vcc, s44, v6
	s_and_saveexec_b64 s[12:13], vcc
	v_ashrrev_i32_e32 v7, 31, v6
	v_lshlrev_b64 v[6:7], 11, v[6:7]
	v_lshl_add_u64 v[6:7], v[4:5], 0, v[6:7]
	s_waitcnt lgkmcnt(2)
	v_bfe_u32 v9, v25, 16, 1
	v_add3_u32 v25, v25, v9, s28
	global_store_short_d16_hi v[6:7], v25, off
	s_or_b64 exec, exec, s[12:13]
	v_add_u32_e32 v6, s14, v34
	v_cmp_gt_i32_e32 vcc, s44, v6
	s_and_saveexec_b64 s[12:13], vcc
	v_ashrrev_i32_e32 v7, 31, v6
	v_lshlrev_b64 v[6:7], 11, v[6:7]
	v_lshl_add_u64 v[6:7], v[4:5], 0, v[6:7]
	s_waitcnt lgkmcnt(1)
	v_bfe_u32 v9, v26, 16, 1
	v_add3_u32 v26, v26, v9, s28
	global_store_short_d16_hi v[6:7], v26, off
	s_or_b64 exec, exec, s[12:13]
	v_add_u32_e32 v6, s14, v35
	v_cmp_gt_i32_e32 vcc, s44, v6
	s_and_saveexec_b64 s[12:13], vcc
	v_ashrrev_i32_e32 v7, 31, v6
	v_lshlrev_b64 v[6:7], 11, v[6:7]
	v_lshl_add_u64 v[6:7], v[4:5], 0, v[6:7]
	s_waitcnt lgkmcnt(0)
	v_bfe_u32 v9, v27, 16, 1
	v_add3_u32 v27, v27, v9, s28
	global_store_short_d16_hi v[6:7], v27, off
	s_or_b64 exec, exec, s[12:13]

; DI void prep_transpose_tile(const float* __restrict__ src, u16* __restrict__ dst, int R, int C, const float* __restrict__ g, int tr, int tc, float* lds) {
;     ...
;   for (int i = tid; i < 4096; i += NTHR) {
;     int r = i >> 6, c = i & 63, gr = tr * 64 + r, gc = tc * 64 + c;
;     float v = 0.f;
;     if (gr < R && gc < C) { v = src[(size_t)gr * C + gc]; if (g) v *= g[gr]; }
;     lds[r * 65 + c] = v;
;   }
.LBB0_41:
	s_mul_i32 s0, s48, 0xba3
	s_lshr_b32 s1, s0, 31
	s_ashr_i32 s11, s0, 17
	s_add_i32 s11, s11, s1
	s_mul_i32 s0, s11, 44
	s_sub_i32 s0, s48, s0
	v_mov_b32_e32 v1, v184
	s_sext_i32_i16 s16, s0
	s_nop 0
	v_cmp_gt_i32_e32 vcc, s22, v1
	v_and_b32_e32 v6, 63, v1
	s_and_saveexec_b64 s[12:13], vcc
	s_cbranch_execz .LBB0_46
	v_readlane_b32 s56, v254, 0
	s_mul_i32 s1, s10, 0xae0000
	v_readlane_b32 s58, v254, 2
	s_mul_hi_i32 s0, s10, 0xae0000
	v_readlane_b32 s59, v254, 3
	s_add_u32 s4, s58, s1
	v_lshl_or_b32 v4, s16, 6, v6
	s_addc_u32 s5, s59, s0
	v_ashrrev_i32_e32 v5, 31, v4
	s_lshl_b32 s17, s11, 6
	v_cmp_gt_i32_e64 s[0:1], s45, v4
	v_lshl_add_u64 v[4:5], v[4:5], 2, s[4:5]
	v_lshl_add_u32 v2, v6, 2, 0
	s_mov_b64 s[14:15], 0
	v_mov_b32_e32 v7, v1
	v_readlane_b32 s57, v254, 1
	v_readlane_b32 s60, v254, 4
	v_readlane_b32 s61, v254, 5
	v_readlane_b32 s62, v254, 6
	v_readlane_b32 s63, v254, 7
	v_readlane_b32 s64, v254, 8
	v_readlane_b32 s65, v254, 9
	v_readlane_b32 s66, v254, 10
	v_readlane_b32 s67, v254, 11
	v_readlane_b32 s68, v254, 12
	v_readlane_b32 s69, v254, 13
	v_readlane_b32 s70, v254, 14
	v_readlane_b32 s71, v254, 15
	v_ashrrev_i32_e32 v36, 6, v1
	v_add_u32_e32 v10, s17, v36
	v_cmp_gt_i32_e64 s[4:5], s44, v10
	v_mad_u32_u24 v28, v36, s26, v2
	v_mov_b32_e32 v20, 0
	s_and_b64 s[4:5], s[4:5], s[0:1]
	s_and_saveexec_b64 s[18:19], s[4:5]
	v_mad_i64_i32 v[10:11], s[4:5], v10, s46, v[4:5]
	global_load_dword v20, v[10:11], off
	s_or_b64 exec, exec, s[18:19]
	v_add_u32_e32 v37, 8, v36
	v_add_u32_e32 v10, s17, v37
	v_cmp_gt_i32_e64 s[4:5], s44, v10
	v_mad_u32_u24 v29, v37, s26, v2
	v_mov_b32_e32 v21, 0
	s_and_b64 s[4:5], s[4:5], s[0:1]
	s_and_saveexec_b64 s[18:19], s[4:5]
	v_mad_i64_i32 v[10:11], s[4:5], v10, s46, v[4:5]
	global_load_dword v21, v[10:11], off
	s_or_b64 exec, exec, s[18:19]
	v_add_u32_e32 v37, 16, v36
	v_add_u32_e32 v10, s17, v37
	v_cmp_gt_i32_e64 s[4:5], s44, v10
	v_mad_u32_u24 v30, v37, s26, v2
	v_mov_b32_e32 v22, 0
	s_and_b64 s[4:5], s[4:5], s[0:1]
	s_and_saveexec_b64 s[18:19], s[4:5]
	v_mad_i64_i32 v[10:11], s[4:5], v10, s46, v[4:5]
	global_load_dword v22, v[10:11], off
	s_or_b64 exec, exec, s[18:19]
	v_add_u32_e32 v37, 24, v36
	v_add_u32_e32 v10, s17, v37
	v_cmp_gt_i32_e64 s[4:5], s44, v10
	v_mad_u32_u24 v31, v37, s26, v2
	v_mov_b32_e32 v23, 0
	s_and_b64 s[4:5], s[4:5], s[0:1]
	s_and_saveexec_b64 s[18:19], s[4:5]
	v_mad_i64_i32 v[10:11], s[4:5], v10, s46, v[4:5]
	global_load_dword v23, v[10:11], off
	s_or_b64 exec, exec, s[18:19]
	v_add_u32_e32 v37, 32, v36
	v_add_u32_e32 v10, s17, v37
	v_cmp_gt_i32_e64 s[4:5], s44, v10
	v_mad_u32_u24 v32, v37, s26, v2
	v_mov_b32_e32 v24, 0
	s_and_b64 s[4:5], s[4:5], s[0:1]
	s_and_saveexec_b64 s[18:19], s[4:5]
	v_mad_i64_i32 v[10:11], s[4:5], v10, s46, v[4:5]
	global_load_dword v24, v[10:11], off
	s_or_b64 exec, exec, s[18:19]
	v_add_u32_e32 v37, 40, v36
	v_add_u32_e32 v10, s17, v37
	v_cmp_gt_i32_e64 s[4:5], s44, v10
	v_mad_u32_u24 v33, v37, s26, v2
	v_mov_b32_e32 v25, 0
	s_and_b64 s[4:5], s[4:5], s[0:1]
	s_and_saveexec_b64 s[18:19], s[4:5]
	v_mad_i64_i32 v[10:11], s[4:5], v10, s46, v[4:5]
	global_load_dword v25, v[10:11], off
	s_or_b64 exec, exec, s[18:19]
	v_add_u32_e32 v37, 48, v36
	v_add_u32_e32 v10, s17, v37
	v_cmp_gt_i32_e64 s[4:5], s44, v10
	v_mad_u32_u24 v34, v37, s26, v2
	v_mov_b32_e32 v26, 0
	s_and_b64 s[4:5], s[4:5], s[0:1]
	s_and_saveexec_b64 s[18:19], s[4:5]
	v_mad_i64_i32 v[10:11], s[4:5], v10, s46, v[4:5]
	global_load_dword v26, v[10:11], off
	s_or_b64 exec, exec, s[18:19]
	v_add_u32_e32 v37, 56, v36
	v_add_u32_e32 v10, s17, v37
	v_cmp_gt_i32_e64 s[4:5], s44, v10
	v_mad_u32_u24 v35, v37, s26, v2
	v_mov_b32_e32 v27, 0
	s_and_b64 s[4:5], s[4:5], s[0:1]
	s_and_saveexec_b64 s[18:19], s[4:5]
	v_mad_i64_i32 v[10:11], s[4:5], v10, s46, v[4:5]
	global_load_dword v27, v[10:11], off
	s_or_b64 exec, exec, s[18:19]
	s_waitcnt vmcnt(0)
	ds_write_b32 v28, v20
	ds_write_b32 v29, v21
	ds_write_b32 v30, v22
	ds_write_b32 v31, v23
	ds_write_b32 v32, v24
	ds_write_b32 v33, v25
	ds_write_b32 v34, v26
	ds_write_b32 v35, v27
; DI u16 f2bf(float x) { unsigned u = __float_as_uint(x); u += 0x7fffu + ((u >> 16) & 1u); return (u16)(u >> 16); }
; DI void prep_transpose_tile(const float* __restrict__ src, u16* __restrict__ dst, int R, int C, const float* __restrict__ g, int tr, int tc, float* lds) {
;     ...
;   __syncthreads();
;   for (int i = tid; i < 4096; i += NTHR) {
;     int c = i >> 6, r = i & 63, gr = tr * 64 + r, gc = tc * 64 + c;
;     if (gr < R && gc < C) dst[(size_t)gc * R + gr] = f2bf(lds[r * 65 + c]);
;   }
.LBB0_46:
	s_or_b64 exec, exec, s[12:13]
	s_waitcnt lgkmcnt(0)
	s_barrier
	s_and_saveexec_b64 s[4:5], vcc
	s_cbranch_execz .LBB0_2
	s_mul_i32 s0, s10, 0x570000
	s_mul_hi_i32 s1, s10, 0x570000
	s_add_u32 s0, s34, s0
	v_lshl_or_b32 v4, s11, 6, v6
	s_addc_u32 s1, s35, s1
	v_ashrrev_i32_e32 v5, 31, v4
	s_lshl_b32 s12, s16, 6
	v_cmp_gt_i32_e32 vcc, s44, v4
	v_mad_u32_u24 v2, v6, s26, 0
	v_lshl_add_u64 v[4:5], v[4:5], 1, s[0:1]
	s_mov_b64 s[10:11], 0
	v_ashrrev_i32_e32 v36, 6, v1
	v_mov_b32_e32 v28, v36
	v_lshl_add_u32 v37, v28, 2, v2
	ds_read_b32 v20, v37
	v_add_u32_e32 v29, 8, v36
	v_lshl_add_u32 v37, v29, 2, v2
	ds_read_b32 v21, v37
	v_add_u32_e32 v30, 16, v36
	v_lshl_add_u32 v37, v30, 2, v2
	ds_read_b32 v22, v37
	v_add_u32_e32 v31, 24, v36
	v_lshl_add_u32 v37, v31, 2, v2
	ds_read_b32 v23, v37
	v_add_u32_e32 v32, 32, v36
	v_lshl_add_u32 v37, v32, 2, v2
	ds_read_b32 v24, v37
	v_add_u32_e32 v33, 40, v36
	v_lshl_add_u32 v37, v33, 2, v2
	ds_read_b32 v25, v37
	v_add_u32_e32 v34, 48, v36
	v_lshl_add_u32 v37, v34, 2, v2
	ds_read_b32 v26, v37
	v_add_u32_e32 v35, 56, v36
	v_lshl_add_u32 v37, v35, 2, v2
	ds_read_b32 v27, v37
	v_add_u32_e32 v6, s12, v28
	v_cmp_gt_i32_e64 s[0:1], s45, v6
	s_and_b64 s[14:15], vcc, s[0:1]
	s_and_saveexec_b64 s[0:1], s[14:15]
	v_ashrrev_i32_e32 v7, 31, v6
	v_lshlrev_b64 v[6:7], 11, v[6:7]
	v_lshl_add_u64 v[6:7], v[4:5], 0, v[6:7]
	s_waitcnt lgkmcnt(7)
	v_bfe_u32 v9, v20, 16, 1
	v_add3_u32 v20, v20, v9, s28
	global_store_short_d16_hi v[6:7], v20, off
	s_or_b64 exec, exec, s[0:1]
	v_add_u32_e32 v6, s12, v29
	v_cmp_gt_i32_e64 s[0:1], s45, v6
	s_and_b64 s[14:15], vcc, s[0:1]
	s_and_saveexec_b64 s[0:1], s[14:15]
	v_ashrrev_i32_e32 v7, 31, v6
	v_lshlrev_b64 v[6:7], 11, v[6:7]
	v_lshl_add_u64 v[6:7], v[4:5], 0, v[6:7]
	s_waitcnt lgkmcnt(6)
	v_bfe_u32 v9, v21, 16, 1
	v_add3_u32 v21, v21, v9, s28
	global_store_short_d16_hi v[6:7], v21, off
	s_or_b64 exec, exec, s[0:1]
	v_add_u32_e32 v6, s12, v30
	v_cmp_gt_i32_e64 s[0:1], s45, v6
	s_and_b64 s[14:15], vcc, s[0:1]
	s_and_saveexec_b64 s[0:1], s[14:15]
	v_ashrrev_i32_e32 v7, 31, v6
	v_lshlrev_b64 v[6:7], 11, v[6:7]
	v_lshl_add_u64 v[6:7], v[4:5], 0, v[6:7]
	s_waitcnt lgkmcnt(5)
	v_bfe_u32 v9, v22, 16, 1
	v_add3_u32 v22, v22, v9, s28
	global_store_short_d16_hi v[6:7], v22, off
	s_or_b64 exec, exec, s[0:1]
	v_add_u32_e32 v6, s12, v31
	v_cmp_gt_i32_e64 s[0:1], s45, v6
	s_and_b64 s[14:15], vcc, s[0:1]
	s_and_saveexec_b64 s[0:1], s[14:15]
	v_ashrrev_i32_e32 v7, 31, v6
	v_lshlrev_b64 v[6:7], 11, v[6:7]
	v_lshl_add_u64 v[6:7], v[4:5], 0, v[6:7]
	s_waitcnt lgkmcnt(4)
	v_bfe_u32 v9, v23, 16, 1
	v_add3_u32 v23, v23, v9, s28
	global_store_short_d16_hi v[6:7], v23, off
	s_or_b64 exec, exec, s[0:1]
	v_add_u32_e32 v6, s12, v32
	v_cmp_gt_i32_e64 s[0:1], s45, v6
	s_and_b64 s[14:15], vcc, s[0:1]
	s_and_saveexec_b64 s[0:1], s[14:15]
	v_ashrrev_i32_e32 v7, 31, v6
	v_lshlrev_b64 v[6:7], 11, v[6:7]
	v_lshl_add_u64 v[6:7], v[4:5], 0, v[6:7]
	s_waitcnt lgkmcnt(3)
	v_bfe_u32 v9, v24, 16, 1
	v_add3_u32 v24, v24, v9, s28
	global_store_short_d16_hi v[6:7], v24, off
	s_or_b64 exec, exec, s[0:1]
	v_add_u32_e32 v6, s12, v33
	v_cmp_gt_i32_e64 s[0:1], s45, v6
	s_and_b64 s[14:15], vcc, s[0:1]
	s_and_saveexec_b64 s[0:1], s[14:15]
	v_ashrrev_i32_e32 v7, 31, v6
	v_lshlrev_b64 v[6:7], 11, v[6:7]
	v_lshl_add_u64 v[6:7], v[4:5], 0, v[6:7]
	s_waitcnt lgkmcnt(2)
	v_bfe_u32 v9, v25, 16, 1
	v_add3_u32 v25, v25, v9, s28
	global_store_short_d16_hi v[6:7], v25, off
	s_or_b64 exec, exec, s[0:1]
	v_add_u32_e32 v6, s12, v34
	v_cmp_gt_i32_e64 s[0:1], s45, v6
	s_and_b64 s[14:15], vcc, s[0:1]
	s_and_saveexec_b64 s[0:1], s[14:15]
	v_ashrrev_i32_e32 v7, 31, v6
	v_lshlrev_b64 v[6:7], 11, v[6:7]
	v_lshl_add_u64 v[6:7], v[4:5], 0, v[6:7]
	s_waitcnt lgkmcnt(1)
	v_bfe_u32 v9, v26, 16, 1
	v_add3_u32 v26, v26, v9, s28
	global_store_short_d16_hi v[6:7], v26, off
	s_or_b64 exec, exec, s[0:1]
	v_add_u32_e32 v6, s12, v35
	v_cmp_gt_i32_e64 s[0:1], s45, v6
	s_and_b64 s[14:15], vcc, s[0:1]
	s_and_saveexec_b64 s[0:1], s[14:15]
	v_ashrrev_i32_e32 v7, 31, v6
	v_lshlrev_b64 v[6:7], 11, v[6:7]
	v_lshl_add_u64 v[6:7], v[4:5], 0, v[6:7]
	s_waitcnt lgkmcnt(0)
	v_bfe_u32 v9, v27, 16, 1
	v_add3_u32 v27, v27, v9, s28
	global_store_short_d16_hi v[6:7], v27, off
	s_or_b64 exec, exec, s[0:1]
	s_branch .LBB0_2

; DI unsigned pk2(float lo, float hi) { f32x2 v = {lo, hi}; b16x2 r = __builtin_convertvector(v, b16x2); return __builtin_bit_cast(unsigned, r); }
; DI void phase_prep(const Params& p, char* lds) {
;     ...
;   const size_t gtid = (size_t)blockIdx.x * NTHR + threadIdx.x, gsz = (size_t)gridDim.x * NTHR;
;   u16* xb = (u16*)(p.ws + OFF_XB);
;   for (size_t i = gtid; i < (size_t)T * DM / 8; i += gsz) {
;     f32x4 a = *(const f32x4*)(p.x + i * 8), b = *(const f32x4*)(p.x + i * 8 + 4);
;     u32x4 o = {pk2(a[0], a[1]), pk2(a[2], a[3]), pk2(b[0], b[1]), pk2(b[2], b[3])};
;     *(u32x4*)(xb + i * 8) = o;
;   }
.LBB0_57:
	s_load_dword s4, s[52:53], 0x10
	s_mov_b32 s2, s54
	s_mov_b32 s3, 0
	v_mov_b32_e32 v185, 0
	s_lshl_b64 s[0:1], s[2:3], 9
	v_lshl_add_u64 v[2:3], s[0:1], 0, v[184:185]
	s_waitcnt lgkmcnt(0)
	s_lshr_b32 s0, s4, 16
	s_cmp_lg_u32 s0, 0
	s_cselect_b64 s[0:1], -1, 0
	s_cmp_lg_u64 s[0:1], 0
	s_addc_u32 s6, s74, 0
	v_writelane_b32 v254, s2, 26
	s_mov_b32 s7, s3
	s_mov_b64 s[4:5], 0x400000
	v_writelane_b32 v254, s3, 27
	s_lshl_b64 s[0:1], s[6:7], 9
	v_cmp_gt_u64_e32 vcc, s[4:5], v[2:3]
	s_and_saveexec_b64 s[4:5], vcc
	s_cbranch_execz .LBB0_60
	v_readlane_b32 s2, v254, 26
	v_readlane_b32 s3, v254, 27
	s_lshl_b64 s[8:9], s[2:3], 14
	v_readlane_b32 s12, v254, 0
	v_readlane_b32 s13, v254, 1
	s_add_u32 s8, s12, s8
	v_lshlrev_b32_e32 v4, 5, v184
	v_mov_b32_e32 v5, v185
	s_addc_u32 s9, s13, s9
	v_lshl_add_u64 v[4:5], s[8:9], 0, v[4:5]
	s_lshl_b64 s[8:9], s[6:7], 14
	s_lshl_b64 s[10:11], s[2:3], 13
	s_add_u32 s10, s34, s10
	v_lshlrev_b32_e32 v6, 4, v184
	v_mov_b32_e32 v7, v185
	s_addc_u32 s11, s35, s11
	v_readlane_b32 s14, v254, 2
	v_readlane_b32 s15, v254, 3
	v_lshl_add_u64 v[6:7], s[10:11], 0, v[6:7]
	s_mov_b64 s[10:11], 0x2058100
	v_lshl_add_u64 v[4:5], v[4:5], 0, 16
	v_lshl_add_u64 v[6:7], v[6:7], 0, s[10:11]
	s_lshl_b64 s[10:11], s[6:7], 13
	s_mov_b64 s[12:13], 0
	s_mov_b64 s[14:15], 0x3fffff
	v_mov_b64_e32 v[8:9], v[2:3]
	v_readlane_b32 s16, v254, 4
	v_readlane_b32 s17, v254, 5
	v_readlane_b32 s18, v254, 6
	v_readlane_b32 s19, v254, 7
	v_readlane_b32 s20, v254, 8
	v_readlane_b32 s21, v254, 9
	v_readlane_b32 s22, v254, 10
	v_readlane_b32 s23, v254, 11
	v_readlane_b32 s24, v254, 12
	v_readlane_b32 s25, v254, 13
	v_readlane_b32 s26, v254, 14
	v_readlane_b32 s27, v254, 15
	s_lshl_b64 vcc, s[0:1], 5
	s_cmp_eq_u64 vcc, 0x400000
	s_cbranch_scc0 .LBB0_59
	global_load_dwordx4 v[44:47], v[4:5], off
	global_load_dwordx4 v[40:43], v[4:5], off offset:-16
	v_lshl_add_u64 v[4:5], v[4:5], 0, s[8:9]
	global_load_dwordx4 v[52:55], v[4:5], off
	global_load_dwordx4 v[48:51], v[4:5], off offset:-16
	v_lshl_add_u64 v[4:5], v[4:5], 0, s[8:9]
	global_load_dwordx4 v[60:63], v[4:5], off
	global_load_dwordx4 v[56:59], v[4:5], off offset:-16
	v_lshl_add_u64 v[4:5], v[4:5], 0, s[8:9]
	global_load_dwordx4 v[68:71], v[4:5], off
	global_load_dwordx4 v[64:67], v[4:5], off offset:-16
	v_lshl_add_u64 v[4:5], v[4:5], 0, s[8:9]
	global_load_dwordx4 v[76:79], v[4:5], off
	global_load_dwordx4 v[72:75], v[4:5], off offset:-16
	v_lshl_add_u64 v[4:5], v[4:5], 0, s[8:9]
	global_load_dwordx4 v[84:87], v[4:5], off
	global_load_dwordx4 v[80:83], v[4:5], off offset:-16
	v_lshl_add_u64 v[4:5], v[4:5], 0, s[8:9]
	global_load_dwordx4 v[92:95], v[4:5], off
	global_load_dwordx4 v[88:91], v[4:5], off offset:-16
	v_lshl_add_u64 v[4:5], v[4:5], 0, s[8:9]
	global_load_dwordx4 v[100:103], v[4:5], off
	global_load_dwordx4 v[96:99], v[4:5], off offset:-16
	v_lshl_add_u64 v[4:5], v[4:5], 0, s[8:9]
	s_waitcnt vmcnt(14)
	v_cvt_pk_bf16_f32 v40, v40, v41
	v_cvt_pk_bf16_f32 v41, v42, v43
	v_cvt_pk_bf16_f32 v42, v44, v45
	v_cvt_pk_bf16_f32 v43, v46, v47
	global_store_dwordx4 v[6:7], v[40:43], off
	v_lshl_add_u64 v[6:7], v[6:7], 0, s[10:11]
	global_load_dwordx4 v[44:47], v[4:5], off
	global_load_dwordx4 v[40:43], v[4:5], off offset:-16
	v_lshl_add_u64 v[4:5], v[4:5], 0, s[8:9]
	s_waitcnt vmcnt(15)
	v_cvt_pk_bf16_f32 v48, v48, v49
	v_cvt_pk_bf16_f32 v49, v50, v51
	v_cvt_pk_bf16_f32 v50, v52, v53
	v_cvt_pk_bf16_f32 v51, v54, v55
	global_store_dwordx4 v[6:7], v[48:51], off
	v_lshl_add_u64 v[6:7], v[6:7], 0, s[10:11]
	global_load_dwordx4 v[52:55], v[4:5], off
	global_load_dwordx4 v[48:51], v[4:5], off offset:-16
	v_lshl_add_u64 v[4:5], v[4:5], 0, s[8:9]
	s_waitcnt vmcnt(16)
	v_cvt_pk_bf16_f32 v56, v56, v57
	v_cvt_pk_bf16_f32 v57, v58, v59
	v_cvt_pk_bf16_f32 v58, v60, v61
	v_cvt_pk_bf16_f32 v59, v62, v63
	global_store_dwordx4 v[6:7], v[56:59], off
	v_lshl_add_u64 v[6:7], v[6:7], 0, s[10:11]
	global_load_dwordx4 v[60:63], v[4:5], off
	global_load_dwordx4 v[56:59], v[4:5], off offset:-16
	v_lshl_add_u64 v[4:5], v[4:5], 0, s[8:9]
	s_waitcnt vmcnt(17)
	v_cvt_pk_bf16_f32 v64, v64, v65
	v_cvt_pk_bf16_f32 v65, v66, v67
	v_cvt_pk_bf16_f32 v66, v68, v69
	v_cvt_pk_bf16_f32 v67, v70, v71
	global_store_dwordx4 v[6:7], v[64:67], off
	v_lshl_add_u64 v[6:7], v[6:7], 0, s[10:11]
	global_load_dwordx4 v[68:71], v[4:5], off
	global_load_dwordx4 v[64:67], v[4:5], off offset:-16
	v_lshl_add_u64 v[4:5], v[4:5], 0, s[8:9]
	s_waitcnt vmcnt(18)
	v_cvt_pk_bf16_f32 v72, v72, v73
	v_cvt_pk_bf16_f32 v73, v74, v75
	v_cvt_pk_bf16_f32 v74, v76, v77
	v_cvt_pk_bf16_f32 v75, v78, v79
	global_store_dwordx4 v[6:7], v[72:75], off
	v_lshl_add_u64 v[6:7], v[6:7], 0, s[10:11]
	global_load_dwordx4 v[76:79], v[4:5], off
	global_load_dwordx4 v[72:75], v[4:5], off offset:-16
	v_lshl_add_u64 v[4:5], v[4:5], 0, s[8:9]
	s_waitcnt vmcnt(19)
	v_cvt_pk_bf16_f32 v80, v80, v81
	v_cvt_pk_bf16_f32 v81, v82, v83
	v_cvt_pk_bf16_f32 v82, v84, v85
	v_cvt_pk_bf16_f32 v83, v86, v87
	global_store_dwordx4 v[6:7], v[80:83], off
	v_lshl_add_u64 v[6:7], v[6:7], 0, s[10:11]
	global_load_dwordx4 v[84:87], v[4:5], off
	global_load_dwordx4 v[80:83], v[4:5], off offset:-16
	v_lshl_add_u64 v[4:5], v[4:5], 0, s[8:9]
	s_waitcnt vmcnt(20)
	v_cvt_pk_bf16_f32 v88, v88, v89
	v_cvt_pk_bf16_f32 v89, v90, v91
	v_cvt_pk_bf16_f32 v90, v92, v93
	v_cvt_pk_bf16_f32 v91, v94, v95
	global_store_dwordx4 v[6:7], v[88:91], off
	v_lshl_add_u64 v[6:7], v[6:7], 0, s[10:11]
	global_load_dwordx4 v[92:95], v[4:5], off
	global_load_dwordx4 v[88:91], v[4:5], off offset:-16
	v_lshl_add_u64 v[4:5], v[4:5], 0, s[8:9]
	s_waitcnt vmcnt(21)
; DI unsigned pk2(float lo, float hi) { f32x2 v = {lo, hi}; b16x2 r = __builtin_convertvector(v, b16x2); return __builtin_bit_cast(unsigned, r); }
; DI void phase_prep(const Params& p, char* lds) {
;     ...
;   const size_t gtid = (size_t)blockIdx.x * NTHR + threadIdx.x, gsz = (size_t)gridDim.x * NTHR;
;   u16* xb = (u16*)(p.ws + OFF_XB);
;   for (size_t i = gtid; i < (size_t)T * DM / 8; i += gsz) {
;     f32x4 a = *(const f32x4*)(p.x + i * 8), b = *(const f32x4*)(p.x + i * 8 + 4);
;     u32x4 o = {pk2(a[0], a[1]), pk2(a[2], a[3]), pk2(b[0], b[1]), pk2(b[2], b[3])};
;     *(u32x4*)(xb + i * 8) = o;
;   }
	v_cvt_pk_bf16_f32 v96, v96, v97
	v_cvt_pk_bf16_f32 v97, v98, v99
	v_cvt_pk_bf16_f32 v98, v100, v101
	v_cvt_pk_bf16_f32 v99, v102, v103
	global_store_dwordx4 v[6:7], v[96:99], off
	v_lshl_add_u64 v[6:7], v[6:7], 0, s[10:11]
	global_load_dwordx4 v[100:103], v[4:5], off
	global_load_dwordx4 v[96:99], v[4:5], off offset:-16
	v_lshl_add_u64 v[4:5], v[4:5], 0, s[8:9]
	s_waitcnt vmcnt(21)
	v_cvt_pk_bf16_f32 v40, v40, v41
	v_cvt_pk_bf16_f32 v41, v42, v43
	v_cvt_pk_bf16_f32 v42, v44, v45
	v_cvt_pk_bf16_f32 v43, v46, v47
	global_store_dwordx4 v[6:7], v[40:43], off
	v_lshl_add_u64 v[6:7], v[6:7], 0, s[10:11]
	global_load_dwordx4 v[44:47], v[4:5], off
	global_load_dwordx4 v[40:43], v[4:5], off offset:-16
	v_lshl_add_u64 v[4:5], v[4:5], 0, s[8:9]
	s_waitcnt vmcnt(21)
	v_cvt_pk_bf16_f32 v48, v48, v49
	v_cvt_pk_bf16_f32 v49, v50, v51
	v_cvt_pk_bf16_f32 v50, v52, v53
	v_cvt_pk_bf16_f32 v51, v54, v55
	global_store_dwordx4 v[6:7], v[48:51], off
	v_lshl_add_u64 v[6:7], v[6:7], 0, s[10:11]
	global_load_dwordx4 v[52:55], v[4:5], off
	global_load_dwordx4 v[48:51], v[4:5], off offset:-16
	v_lshl_add_u64 v[4:5], v[4:5], 0, s[8:9]
	s_waitcnt vmcnt(21)
	v_cvt_pk_bf16_f32 v56, v56, v57
	v_cvt_pk_bf16_f32 v57, v58, v59
	v_cvt_pk_bf16_f32 v58, v60, v61
	v_cvt_pk_bf16_f32 v59, v62, v63
	global_store_dwordx4 v[6:7], v[56:59], off
	v_lshl_add_u64 v[6:7], v[6:7], 0, s[10:11]
	global_load_dwordx4 v[60:63], v[4:5], off
	global_load_dwordx4 v[56:59], v[4:5], off offset:-16
	v_lshl_add_u64 v[4:5], v[4:5], 0, s[8:9]
	s_waitcnt vmcnt(21)
	v_cvt_pk_bf16_f32 v64, v64, v65
	v_cvt_pk_bf16_f32 v65, v66, v67
	v_cvt_pk_bf16_f32 v66, v68, v69
	v_cvt_pk_bf16_f32 v67, v70, v71
	global_store_dwordx4 v[6:7], v[64:67], off
	v_lshl_add_u64 v[6:7], v[6:7], 0, s[10:11]
	global_load_dwordx4 v[68:71], v[4:5], off
	global_load_dwordx4 v[64:67], v[4:5], off offset:-16
	v_lshl_add_u64 v[4:5], v[4:5], 0, s[8:9]
	s_waitcnt vmcnt(21)
	v_cvt_pk_bf16_f32 v72, v72, v73
	v_cvt_pk_bf16_f32 v73, v74, v75
	v_cvt_pk_bf16_f32 v74, v76, v77
	v_cvt_pk_bf16_f32 v75, v78, v79
	global_store_dwordx4 v[6:7], v[72:75], off
	v_lshl_add_u64 v[6:7], v[6:7], 0, s[10:11]
	global_load_dwordx4 v[76:79], v[4:5], off
	global_load_dwordx4 v[72:75], v[4:5], off offset:-16
	v_lshl_add_u64 v[4:5], v[4:5], 0, s[8:9]
	s_waitcnt vmcnt(21)
	v_cvt_pk_bf16_f32 v80, v80, v81
	v_cvt_pk_bf16_f32 v81, v82, v83
	v_cvt_pk_bf16_f32 v82, v84, v85
	v_cvt_pk_bf16_f32 v83, v86, v87
	global_store_dwordx4 v[6:7], v[80:83], off
	v_lshl_add_u64 v[6:7], v[6:7], 0, s[10:11]
	global_load_dwordx4 v[84:87], v[4:5], off
	global_load_dwordx4 v[80:83], v[4:5], off offset:-16
	v_lshl_add_u64 v[4:5], v[4:5], 0, s[8:9]
	s_waitcnt vmcnt(21)
	v_cvt_pk_bf16_f32 v88, v88, v89
	v_cvt_pk_bf16_f32 v89, v90, v91
	v_cvt_pk_bf16_f32 v90, v92, v93
	v_cvt_pk_bf16_f32 v91, v94, v95
	global_store_dwordx4 v[6:7], v[88:91], off
	v_lshl_add_u64 v[6:7], v[6:7], 0, s[10:11]
	global_load_dwordx4 v[92:95], v[4:5], off
	global_load_dwordx4 v[88:91], v[4:5], off offset:-16
	v_lshl_add_u64 v[4:5], v[4:5], 0, s[8:9]
	s_waitcnt vmcnt(21)
	v_cvt_pk_bf16_f32 v96, v96, v97
	v_cvt_pk_bf16_f32 v97, v98, v99
	v_cvt_pk_bf16_f32 v98, v100, v101
	v_cvt_pk_bf16_f32 v99, v102, v103
	global_store_dwordx4 v[6:7], v[96:99], off
	v_lshl_add_u64 v[6:7], v[6:7], 0, s[10:11]
	global_load_dwordx4 v[100:103], v[4:5], off
	global_load_dwordx4 v[96:99], v[4:5], off offset:-16
	v_lshl_add_u64 v[4:5], v[4:5], 0, s[8:9]
	s_waitcnt vmcnt(21)
	v_cvt_pk_bf16_f32 v40, v40, v41
	v_cvt_pk_bf16_f32 v41, v42, v43
	v_cvt_pk_bf16_f32 v42, v44, v45
	v_cvt_pk_bf16_f32 v43, v46, v47
	global_store_dwordx4 v[6:7], v[40:43], off
	v_lshl_add_u64 v[6:7], v[6:7], 0, s[10:11]
	global_load_dwordx4 v[44:47], v[4:5], off
	global_load_dwordx4 v[40:43], v[4:5], off offset:-16
	v_lshl_add_u64 v[4:5], v[4:5], 0, s[8:9]
	s_waitcnt vmcnt(21)
	v_cvt_pk_bf16_f32 v48, v48, v49
	v_cvt_pk_bf16_f32 v49, v50, v51
	v_cvt_pk_bf16_f32 v50, v52, v53
	v_cvt_pk_bf16_f32 v51, v54, v55
	global_store_dwordx4 v[6:7], v[48:51], off
	v_lshl_add_u64 v[6:7], v[6:7], 0, s[10:11]
	global_load_dwordx4 v[52:55], v[4:5], off
	global_load_dwordx4 v[48:51], v[4:5], off offset:-16
	v_lshl_add_u64 v[4:5], v[4:5], 0, s[8:9]
	s_waitcnt vmcnt(21)
; DI unsigned pk2(float lo, float hi) { f32x2 v = {lo, hi}; b16x2 r = __builtin_convertvector(v, b16x2); return __builtin_bit_cast(unsigned, r); }
; DI void phase_prep(const Params& p, char* lds) {
;     ...
;   const size_t gtid = (size_t)blockIdx.x * NTHR + threadIdx.x, gsz = (size_t)gridDim.x * NTHR;
;   u16* xb = (u16*)(p.ws + OFF_XB);
;   for (size_t i = gtid; i < (size_t)T * DM / 8; i += gsz) {
;     f32x4 a = *(const f32x4*)(p.x + i * 8), b = *(const f32x4*)(p.x + i * 8 + 4);
;     u32x4 o = {pk2(a[0], a[1]), pk2(a[2], a[3]), pk2(b[0], b[1]), pk2(b[2], b[3])};
;     *(u32x4*)(xb + i * 8) = o;
;   }
	v_cvt_pk_bf16_f32 v56, v56, v57
	v_cvt_pk_bf16_f32 v57, v58, v59
	v_cvt_pk_bf16_f32 v58, v60, v61
	v_cvt_pk_bf16_f32 v59, v62, v63
	global_store_dwordx4 v[6:7], v[56:59], off
	v_lshl_add_u64 v[6:7], v[6:7], 0, s[10:11]
	global_load_dwordx4 v[60:63], v[4:5], off
	global_load_dwordx4 v[56:59], v[4:5], off offset:-16
	v_lshl_add_u64 v[4:5], v[4:5], 0, s[8:9]
	s_waitcnt vmcnt(21)
	v_cvt_pk_bf16_f32 v64, v64, v65
	v_cvt_pk_bf16_f32 v65, v66, v67
	v_cvt_pk_bf16_f32 v66, v68, v69
	v_cvt_pk_bf16_f32 v67, v70, v71
	global_store_dwordx4 v[6:7], v[64:67], off
	v_lshl_add_u64 v[6:7], v[6:7], 0, s[10:11]
	global_load_dwordx4 v[68:71], v[4:5], off
	global_load_dwordx4 v[64:67], v[4:5], off offset:-16
	v_lshl_add_u64 v[4:5], v[4:5], 0, s[8:9]
	s_waitcnt vmcnt(21)
	v_cvt_pk_bf16_f32 v72, v72, v73
	v_cvt_pk_bf16_f32 v73, v74, v75
	v_cvt_pk_bf16_f32 v74, v76, v77
	v_cvt_pk_bf16_f32 v75, v78, v79
	global_store_dwordx4 v[6:7], v[72:75], off
	v_lshl_add_u64 v[6:7], v[6:7], 0, s[10:11]
	global_load_dwordx4 v[76:79], v[4:5], off
	global_load_dwordx4 v[72:75], v[4:5], off offset:-16
	v_lshl_add_u64 v[4:5], v[4:5], 0, s[8:9]
	s_waitcnt vmcnt(21)
	v_cvt_pk_bf16_f32 v80, v80, v81
	v_cvt_pk_bf16_f32 v81, v82, v83
	v_cvt_pk_bf16_f32 v82, v84, v85
	v_cvt_pk_bf16_f32 v83, v86, v87
	global_store_dwordx4 v[6:7], v[80:83], off
	v_lshl_add_u64 v[6:7], v[6:7], 0, s[10:11]
	global_load_dwordx4 v[84:87], v[4:5], off
	global_load_dwordx4 v[80:83], v[4:5], off offset:-16
	v_lshl_add_u64 v[4:5], v[4:5], 0, s[8:9]
	s_waitcnt vmcnt(21)
	v_cvt_pk_bf16_f32 v88, v88, v89
	v_cvt_pk_bf16_f32 v89, v90, v91
	v_cvt_pk_bf16_f32 v90, v92, v93
	v_cvt_pk_bf16_f32 v91, v94, v95
	global_store_dwordx4 v[6:7], v[88:91], off
	v_lshl_add_u64 v[6:7], v[6:7], 0, s[10:11]
	global_load_dwordx4 v[92:95], v[4:5], off
	global_load_dwordx4 v[88:91], v[4:5], off offset:-16
	v_lshl_add_u64 v[4:5], v[4:5], 0, s[8:9]
	s_waitcnt vmcnt(21)
	v_cvt_pk_bf16_f32 v96, v96, v97
	v_cvt_pk_bf16_f32 v97, v98, v99
	v_cvt_pk_bf16_f32 v98, v100, v101
	v_cvt_pk_bf16_f32 v99, v102, v103
	global_store_dwordx4 v[6:7], v[96:99], off
	v_lshl_add_u64 v[6:7], v[6:7], 0, s[10:11]
	global_load_dwordx4 v[100:103], v[4:5], off
	global_load_dwordx4 v[96:99], v[4:5], off offset:-16
	v_lshl_add_u64 v[4:5], v[4:5], 0, s[8:9]
	s_waitcnt vmcnt(21)
	v_cvt_pk_bf16_f32 v40, v40, v41
	v_cvt_pk_bf16_f32 v41, v42, v43
	v_cvt_pk_bf16_f32 v42, v44, v45
	v_cvt_pk_bf16_f32 v43, v46, v47
	global_store_dwordx4 v[6:7], v[40:43], off
	v_lshl_add_u64 v[6:7], v[6:7], 0, s[10:11]
	s_waitcnt vmcnt(19)
	v_cvt_pk_bf16_f32 v48, v48, v49
	v_cvt_pk_bf16_f32 v49, v50, v51
	v_cvt_pk_bf16_f32 v50, v52, v53
	v_cvt_pk_bf16_f32 v51, v54, v55
	global_store_dwordx4 v[6:7], v[48:51], off
	v_lshl_add_u64 v[6:7], v[6:7], 0, s[10:11]
	s_waitcnt vmcnt(17)
	v_cvt_pk_bf16_f32 v56, v56, v57
	v_cvt_pk_bf16_f32 v57, v58, v59
	v_cvt_pk_bf16_f32 v58, v60, v61
	v_cvt_pk_bf16_f32 v59, v62, v63
	global_store_dwordx4 v[6:7], v[56:59], off
	v_lshl_add_u64 v[6:7], v[6:7], 0, s[10:11]
	s_waitcnt vmcnt(15)
	v_cvt_pk_bf16_f32 v64, v64, v65
	v_cvt_pk_bf16_f32 v65, v66, v67
	v_cvt_pk_bf16_f32 v66, v68, v69
	v_cvt_pk_bf16_f32 v67, v70, v71
	global_store_dwordx4 v[6:7], v[64:67], off
	v_lshl_add_u64 v[6:7], v[6:7], 0, s[10:11]
	s_waitcnt vmcnt(13)
	v_cvt_pk_bf16_f32 v72, v72, v73
	v_cvt_pk_bf16_f32 v73, v74, v75
	v_cvt_pk_bf16_f32 v74, v76, v77
	v_cvt_pk_bf16_f32 v75, v78, v79
	global_store_dwordx4 v[6:7], v[72:75], off
	v_lshl_add_u64 v[6:7], v[6:7], 0, s[10:11]
	s_waitcnt vmcnt(11)
	v_cvt_pk_bf16_f32 v80, v80, v81
	v_cvt_pk_bf16_f32 v81, v82, v83
	v_cvt_pk_bf16_f32 v82, v84, v85
	v_cvt_pk_bf16_f32 v83, v86, v87
	global_store_dwordx4 v[6:7], v[80:83], off
	v_lshl_add_u64 v[6:7], v[6:7], 0, s[10:11]
	s_waitcnt vmcnt(9)
	v_cvt_pk_bf16_f32 v88, v88, v89
	v_cvt_pk_bf16_f32 v89, v90, v91
	v_cvt_pk_bf16_f32 v90, v92, v93
	v_cvt_pk_bf16_f32 v91, v94, v95
	global_store_dwordx4 v[6:7], v[88:91], off
	v_lshl_add_u64 v[6:7], v[6:7], 0, s[10:11]
	s_waitcnt vmcnt(7)
	v_cvt_pk_bf16_f32 v96, v96, v97
	v_cvt_pk_bf16_f32 v97, v98, v99
	v_cvt_pk_bf16_f32 v98, v100, v101
	v_cvt_pk_bf16_f32 v99, v102, v103
	global_store_dwordx4 v[6:7], v[96:99], off
	v_lshl_add_u64 v[6:7], v[6:7], 0, s[10:11]
	s_branch .LBB0_60
